# scan q/k chunk tiles staged through registers (4 dwordx4 loads one step ahead + 4 ds_write_b128 before B2) instead of 4 LDS-DMA loads; on top of the no-setprio version
# speedup vs baseline: 1.0116x; 1.0116x over previous
; __device__ __forceinline__ void gla_scan_phase2(LAS unsigned char* lds, const bf16_t* proj, const float* gbuf, const float* wgu  , const float* bg  ,
;                                                 bf16_t* ob0, bf16_t* ob1) {
;     ...
;         if (wave < 4) {
;             const int d = tid & 127, seg = (tid >> 7) & 1;
;             const int zd = wave;
;             bf16x8 wbh, wbl;
;             {
;                 unsigned hi_[4], lo_[4];
; #pragma unroll
;                 for (int q = 0; q < 4; ++q) {
;                     const float w0 = wgu[(size_t)(dir * 16 + 8 * hh + 2 * q) * 512 + h * 128 + 32 * zd + r], w1 = wgu[(size_t)(dir * 16 + 8 * hh + 2 * q + 1) * 512 + h * 128 + 32 * zd + r];
;                     hi_[q] = pk2(w0, w1); lo_[q] = pk2(w0 - bflo(hi_[q]), w1 - bfhi(hi_[q]));
;                 }
;                 wbh = __builtin_bit_cast(bf16x8, (u32x4){hi_[0], hi_[1], hi_[2], hi_[3]}); wbl = __builtin_bit_cast(bf16x8, (u32x4){lo_[0], lo_[1], lo_[2], lo_[3]});
;             }
;             const float zbias = bg[dir * 512 + h * 128 + 32 * zd + r];
;             const __amdgpu_buffer_rsrc_t prs = __builtin_amdgcn_make_buffer_rsrc((void*)proj, 0, (unsigned)((size_t)MTOK * GINP * 2), 0x00020000);
;             const unsigned qvoff = (unsigned)((16 * seg * GINP + h * 128 + d) * 2), vvoff = (unsigned)((16 * seg * GINP + 1024 + h * 256 + 2 * d) * 2);
;             f32x4 gna, gnb;
;             { const float* grow = gbuf + (size_t)(b * SEQ + (dir ? NCH - 1 : 0) * CH + r) * 32 + dir * 16 + 8 * hh; gna = *(const f32x4*)grow; gnb = *(const f32x4*)(grow + 4); }
;             for (int n = 0; n <= NCH; ++n) {
;                 if (n < NCH) {
;                     const int tok0 = b * SEQ + (dir ? NCH - 1 - n : n) * CH;
;                     LAS unsigned char* set = lds + (n & 1) * G2_SET;
;                     const f32x4 ga = gna, gb = gnb;
;                     const unsigned srow = (unsigned)tok0 * (unsigned)(GINP * 2);
;                     unsigned short qv[16], kv[16];
; #pragma unroll
;                     for (int ii = 0; ii < 16; ++ii) { qv[ii] = __builtin_amdgcn_raw_buffer_load_b16(prs, qvoff, srow + (unsigned)(ii * GINP * 2), 0);
;                                                        kv[ii] = __builtin_amdgcn_raw_buffer_load_b16(prs, qvoff + 1024u, srow + (unsigned)(ii * GINP * 2), 0); }
;                     unsigned vw[16];
; #pragma unroll
.LBB0_217:
	s_and_b64 vcc, exec, s[6:7]
	s_cbranch_vccz .LBB0_212
	s_nop 7
	v_lshl_or_b32 v0, s8, 13, v198
	s_lshl_b32 s0, s15, 7
	v_or_b32_e32 v0, s0, v0
	v_lshlrev_b32_e32 v160, 2, v0
	v_lshl_add_u64 v[0:1], s[16:17], 0, v[160:161]
	v_lshl_add_u64 v[0:1], s[22:23], 2, v[0:1]
	v_mov_b32_e32 v193, v161
	v_lshl_add_u64 v[0:1], v[0:1], 0, v[192:193]
	global_load_dword v2, v[0:1], off
	global_load_dword v3, v[0:1], off offset:2048
	s_movk_i32 s6, 0x1000
	s_lshl_b32 s9, s9, 11
	v_lshlrev_b32_e32 v160, 2, v188
	s_mov_b32 s20, 0
	v_or_b32_e32 v52, s9, v186
	s_waitcnt vmcnt(0)
	v_cvt_pk_bf16_f32 v32, v2, v3
	v_lshlrev_b32_e32 v4, 16, v32
	v_and_b32_e32 v5, 0xffff0000, v32
	v_pk_add_f32 v[2:3], v[2:3], v[4:5] neg_lo:[0,1] neg_hi:[0,1]
	s_nop 0
	v_cvt_pk_bf16_f32 v36, v2, v3
	v_add_co_u32_e32 v2, vcc, s6, v0
	s_movk_i32 s6, 0x2000
	s_nop 0
	v_addc_co_u32_e32 v3, vcc, 0, v1, vcc
	v_add_co_u32_e32 v4, vcc, s6, v0
	s_movk_i32 s6, 0x3000
	s_nop 0
	v_addc_co_u32_e32 v5, vcc, 0, v1, vcc
	global_load_dword v6, v[4:5], off offset:-4096
	global_load_dword v7, v[2:3], off offset:2048
	v_add_co_u32_e32 v0, vcc, s6, v0
	s_lshl_b32 s6, s8, 9
	s_nop 0
	v_addc_co_u32_e32 v1, vcc, 0, v1, vcc
	s_or_b32 s6, s0, s6
	s_cmp_lg_u32 s8, 0
	s_cselect_b64 s[68:69], -1, 0
	s_cmp_eq_u32 s8, 0
	s_cselect_b64 s[48:49], -1, 0
	s_waitcnt vmcnt(0)
	v_cvt_pk_bf16_f32 v33, v6, v7
	v_lshlrev_b32_e32 v2, 16, v33
	v_and_b32_e32 v3, 0xffff0000, v33
	v_pk_add_f32 v[2:3], v[6:7], v[2:3] neg_lo:[0,1] neg_hi:[0,1]
	s_nop 0
	v_cvt_pk_bf16_f32 v37, v2, v3
	global_load_dword v2, v[4:5], off
	global_load_dword v3, v[4:5], off offset:2048
	s_waitcnt vmcnt(0)
	v_cvt_pk_bf16_f32 v34, v2, v3
	v_lshlrev_b32_e32 v4, 16, v34
	v_and_b32_e32 v5, 0xffff0000, v34
	v_pk_add_f32 v[2:3], v[2:3], v[4:5] neg_lo:[0,1] neg_hi:[0,1]
	s_nop 0
	v_cvt_pk_bf16_f32 v38, v2, v3
	global_load_dword v2, v[0:1], off
	global_load_dword v3, v[0:1], off offset:2048
	s_waitcnt vmcnt(0)
	v_cvt_pk_bf16_f32 v35, v2, v3
	v_lshlrev_b32_e32 v0, 16, v35
	v_and_b32_e32 v1, 0xffff0000, v35
	v_pk_add_f32 v[0:1], v[2:3], v[0:1] neg_lo:[0,1] neg_hi:[0,1]
	s_nop 0
	v_cvt_pk_bf16_f32 v39, v0, v1
	v_add_u32_e32 v0, s6, v199
	v_ashrrev_i32_e32 v1, 31, v0
	v_lshl_add_u64 v[0:1], v[0:1], 2, s[18:19]
	global_load_dword v0, v[0:1], off
	v_or_b32_e32 v1, s0, v200
	s_and_b64 s[6:7], s[48:49], exec
	v_lshlrev_b32_e32 v50, 1, v1
	v_lshl_or_b32 v1, s15, 9, v213
	s_cselect_b32 s0, 0, 0x7e0
	v_or_b32_e32 v51, 0x800, v1
	v_or_b32_e32 v1, s0, v186
	v_or_b32_e32 v2, s9, v1
	v_ashrrev_i32_e32 v3, 31, v2
	v_readlane_b32 s6, v253, 19
	v_lshlrev_b64 v[2:3], 7, v[2:3]
	v_readlane_b32 s7, v253, 20
	s_lshl_b32 s28, s8, 6
	v_lshl_add_u64 v[48:49], v[190:191], 0, s[28:29]
	v_lshl_add_u64 v[2:3], s[6:7], 0, v[2:3]
	v_lshl_add_u64 v[2:3], v[2:3], 0, s[28:29]
	v_lshl_add_u64 v[2:3], v[2:3], 0, v[160:161]
	global_load_dwordx4 v[40:43], v[2:3], off offset:16
	global_load_dwordx4 v[44:47], v[2:3], off
	v_or_b32_e32 v53, 0x400, v50
	s_xor_b64 s[50:51], s[40:41], s[48:49]
	s_xor_b64 s[52:53], s[42:43], s[48:49]
	s_xor_b64 s[54:55], s[44:45], s[48:49]
	s_xor_b64 s[56:57], s[46:47], s[48:49]
	s_mov_b32 s8, 63
	s_waitcnt vmcnt(2)
	v_mov_b32_e32 v1, v0
	v_mov_b32_e32 v2, v0
	v_mov_b32_e32 v3, v0
	v_mov_b32_e32 v4, v0
	v_mov_b32_e32 v5, v0
	v_mov_b32_e32 v6, v0
	v_mov_b32_e32 v7, v0
	v_mov_b32_e32 v8, v0
	v_mov_b32_e32 v9, v0
	v_mov_b32_e32 v10, v0
	v_mov_b32_e32 v11, v0
	v_mov_b32_e32 v12, v0
	v_mov_b32_e32 v13, v0
	v_mov_b32_e32 v14, v0
	v_mov_b32_e32 v15, v0
	v_and_b32_e32 v171, 7, v179
	v_lshrrev_b32_e32 v175, 3, v179
	v_mul_u32_u24_e32 v176, 0x6800, v171
	v_lshl_add_u32 v176, v175, 4, v176
	s_lshl_b32 s0, s15, 9
	s_addk_i32 s0, 0x800
	v_add_u32_e32 v176, s0, v176
	v_mul_u32_u24_e32 v177, 0x280, v175
	v_lshl_add_u32 v177, v171, 3, v177
	v_and_b32_e32 v172, 15, v179
	v_lshlrev_b32_e32 v172, 4, v172
	v_bfe_u32 v174, v179, 4, 2
	v_lshrrev_b32_e32 v173, 6, v179
	v_lshl_add_u32 v174, v173, 3, v174
	v_mul_u32_u24_e32 v174, 0x1a00, v174
	v_add_u32_e32 v172, v172, v174
	s_lshl_b32 s0, s15, 8
	v_add_u32_e32 v172, s0, v172
	v_lshlrev_b32_e32 v174, 11, v173
	v_add_u32_e32 v174, 0x1b600, v174
	v_and_b32_e32 v250, 63, v179
	v_lshl_add_u32 v250, v250, 4, v174
	v_and_b32_e32 v173, 0x7f, v179
	v_lshlrev_b32_e32 v173, 1, v173
	v_bfe_u32 v175, v179, 7, 1
	v_lshl_add_u32 v173, v175, 12, v173
	v_add_u32_e32 v173, 0x1b600, v173
	s_and_b64 s[6:7], s[48:49], exec
	s_cselect_b32 s0, s20, s8
	s_lshl_b32 s0, s0, 5
	s_add_i32 s0, s0, s9
	s_mulk_i32 s0, 0x1a00
	s_nop 0
	s_add_u32 s78, s64, s0
	s_addc_u32 s79, s65, 0
	s_add_u32 s80, s78, 0x6800
	s_addc_u32 s81, s79, 0
	s_add_u32 s82, s78, 0x400
	s_addc_u32 s83, s79, 0
	s_add_u32 s24, s80, 0x400
	s_addc_u32 s25, s81, 0
	global_load_dwordx4 v[234:237], v172, s[78:79]
	global_load_dwordx4 v[238:241], v172, s[80:81]
	global_load_dwordx4 v[242:245], v172, s[82:83]
	global_load_dwordx4 v[246:249], v172, s[24:25]
	s_branch .LBB0_220
.LBB0_219:
	s_or_b64 exec, exec, s[6:7]
	s_mov_b32 s21, 0x5040100
	s_mov_b32 s24, 0x7060302
	v_add_u32_e32 v171, s15, v177
	s_waitcnt vmcnt(2)
	v_perm_b32 v16, v58, v54, s21
	v_perm_b32 v17, v66, v62, s21
	v_perm_b32 v18, v58, v54, s24
	v_perm_b32 v19, v66, v62, s24
	v_perm_b32 v20, v59, v55, s21
	v_perm_b32 v21, v67, v63, s21
	v_perm_b32 v22, v59, v55, s24
	v_perm_b32 v23, v67, v63, s24
	v_perm_b32 v24, v60, v56, s21
	v_perm_b32 v25, v68, v64, s21
	v_perm_b32 v26, v60, v56, s24
	v_perm_b32 v27, v68, v64, s24
	v_perm_b32 v28, v61, v57, s21
	v_perm_b32 v29, v69, v65, s21
	v_perm_b32 v30, v61, v57, s24
	v_perm_b32 v31, v69, v65, s24
	ds_write_b64 v171, v[16:17] offset:18944
	ds_write_b64 v171, v[18:19] offset:19024
	ds_write_b64 v171, v[20:21] offset:19104
	ds_write_b64 v171, v[22:23] offset:19184
	ds_write_b64 v171, v[24:25] offset:19264
	ds_write_b64 v171, v[26:27] offset:19344
	ds_write_b64 v171, v[28:29] offset:19424
	ds_write_b64 v171, v[30:31] offset:19504
	s_waitcnt lgkmcnt(0)
	s_barrier
	s_cmp_eq_u32 s20, 63
	s_cbranch_scc1 .Lg2dma_skip
	s_and_b64 s[6:7], s[48:49], exec
	s_cselect_b32 s0, s20, s8
	s_cselect_b32 s6, 1, -1
	s_add_i32 s0, s0, s6
	s_lshl_b32 s0, s0, 5
	s_add_i32 s0, s0, s9
	s_mulk_i32 s0, 0x1a00
	s_nop 0
	s_add_u32 s78, s64, s0
	s_addc_u32 s79, s65, 0
	s_add_u32 s80, s78, 0x6800
	s_addc_u32 s81, s79, 0
	s_add_u32 s82, s78, 0x400
	s_addc_u32 s83, s79, 0
	s_add_u32 s24, s80, 0x400
	s_addc_u32 s25, s81, 0
	global_load_dwordx4 v[234:237], v172, s[78:79]
	global_load_dwordx4 v[238:241], v172, s[80:81]
	global_load_dwordx4 v[242:245], v172, s[82:83]
	global_load_dwordx4 v[246:249], v172, s[24:25]

; #define LAS __attribute__((address_space(3)))
; __device__ __forceinline__ float bf2f(unsigned u16) { return __uint_as_float(u16 << 16); }
; #define G2_BAR() do { asm volatile("s_waitcnt lgkmcnt(0)" ::: "memory"); __builtin_amdgcn_s_barrier(); asm volatile("" ::: "memory"); } while (0)
; __device__ __forceinline__ void gla_scan_phase2(LAS unsigned char* lds, const bf16_t* proj, const float* gbuf, const float* wgu  , const float* bg  ,
;                                                 bf16_t* ob0, bf16_t* ob1) {
;     ...
;                     if (dir == 0) {
; #pragma unroll
;                         for (int ii = 1; ii < 16; ++ii) cs[ii] += cs[ii - 1];
;                         *(LAS float*)(lds + G2_SEG + (seg * 128 + d) * 4) = cs[15];
;                     } else {
; #pragma unroll
;     ...
;                         *(LAS float*)(lds + G2_SEG + (seg * 128 + d) * 4) = cs[0];
;                     }
;                     G2_BAR();
;                     {
;                         const float t0 = *(const LAS float*)(lds + G2_SEG + d * 4), t1 = *(const LAS float*)(lds + G2_SEG + (128 + d) * 4);
;                         const float prefix = dir == 0 ? (seg ? t0 : 0.f) : (seg ? 0.f : t1);
;                         const float ebl = __builtin_amdgcn_exp2f(t0 + t1);
;                         unsigned kd[8];
; #pragma unroll
;                         for (int ii = 0; ii < 16; ii += 2) {
;                             const float e0 = __builtin_amdgcn_exp2f(prefix + cs[ii]), e1 = __builtin_amdgcn_exp2f(prefix + cs[ii + 1]);
;                             const float q0 = bf2f(qv[ii]), q1 = bf2f(qv[ii + 1]);
.LBB0_225:
	s_waitcnt vmcnt(6)
	ds_write_b128 v250, v[234:237]
	ds_write_b128 v250, v[238:241] offset:1024
	ds_write_b128 v250, v[242:245] offset:8192
	ds_write_b128 v250, v[246:249] offset:9216
	ds_write_b32 v231, v115
	s_waitcnt lgkmcnt(0)
	s_barrier
	v_add_u32_e32 v25, s11, v202
	ds_read2st64_b32 v[104:105], v25 offset1:2
	ds_read_u16 v98, v173
	ds_read_u16 v100, v173 offset:256
	ds_read_u16 v94, v173 offset:512
	ds_read_u16 v96, v173 offset:768
	ds_read_u16 v90, v173 offset:1024
	ds_read_u16 v92, v173 offset:1280
	ds_read_u16 v82, v173 offset:1536
	ds_read_u16 v84, v173 offset:1792
	ds_read_u16 v99, v173 offset:8192
	ds_read_u16 v101, v173 offset:8448
	ds_read_u16 v95, v173 offset:8704
	ds_read_u16 v97, v173 offset:8960
	ds_read_u16 v91, v173 offset:9216
	ds_read_u16 v93, v173 offset:9472
	ds_read_u16 v83, v173 offset:9728
	ds_read_u16 v85, v173 offset:9984
	ds_read_u16 v86, v173 offset:2048
	ds_read_u16 v88, v173 offset:2304
	ds_read_u16 v78, v173 offset:2560
	ds_read_u16 v80, v173 offset:2816
	ds_read_u16 v74, v173 offset:3072
	ds_read_u16 v76, v173 offset:3328
	ds_read_u16 v70, v173 offset:3584
	ds_read_u16 v72, v173 offset:3840
	ds_read_u16 v87, v173 offset:10240
	ds_read_u16 v89, v173 offset:10496
	ds_read_u16 v79, v173 offset:10752
	ds_read_u16 v81, v173 offset:11008
	ds_read_u16 v75, v173 offset:11264
	ds_read_u16 v77, v173 offset:11520
	ds_read_u16 v71, v173 offset:11776
	ds_read_u16 v73, v173 offset:12032
	s_bitcmp1_b32 s20, 0
	s_cselect_b32 s0, 0xa800, 0
	s_waitcnt lgkmcnt(0)
	v_lshlrev_b32_e32 v111, 16, v100
	s_add_i32 s15, s0, 0
	s_waitcnt lgkmcnt(0)
; #define LAS __attribute__((address_space(3)))
; __device__ __forceinline__ unsigned pk2(float lo, float hi) { f32x2 v = {lo, hi}; bf16x2_t b = __builtin_convertvector(v, bf16x2_t); return __builtin_bit_cast(unsigned, b); }
; __device__ __forceinline__ float bf2f(unsigned u16) { return __uint_as_float(u16 << 16); }
; __device__ __forceinline__ void gla_scan_phase2(LAS unsigned char* lds, const bf16_t* proj, const float* gbuf, const float* wgu  , const float* bg  ,
;                                                 bf16_t* ob0, bf16_t* ob1) {
;     ...
;                         unsigned kd[8];
; #pragma unroll
;                         for (int ii = 0; ii < 16; ii += 2) {
;                             const float e0 = __builtin_amdgcn_exp2f(prefix + cs[ii]), e1 = __builtin_amdgcn_exp2f(prefix + cs[ii + 1]);
;                             const float q0 = bf2f(qv[ii]), q1 = bf2f(qv[ii + 1]);
;                             const float k0 = bf2f(kv[ii]) * __builtin_amdgcn_rcpf(e0), k1 = bf2f(kv[ii + 1]) * __builtin_amdgcn_rcpf(e1);
;                             const unsigned qd = pk2(q0 * e0, q1 * e1);
;                             const unsigned ki = pk2(k0, k1);
;                             kd[ii >> 1] = pk2(k0 * ebl, k1 * ebl);
;                             const int i0 = 16 * seg + ii;
;                             *(LAS unsigned short*)(set + G2_QD + i0 * 272 + d * 2) = (unsigned short)(qd & 0xffffu);
;                             *(LAS unsigned short*)(set + G2_QD + (i0 + 1) * 272 + d * 2) = (unsigned short)(qd >> 16);
;                             *(LAS unsigned short*)(lds + G2_KI + i0 * 272 + d * 2) = (unsigned short)(ki & 0xffffu);
;                             *(LAS unsigned short*)(lds + G2_KI + (i0 + 1) * 272 + d * 2) = (unsigned short)(ki >> 16);
;                         }
;                         *(LAS u32x4*)(set + G2_KDT + d * 80 + seg * 32) = (u32x4){kd[0], kd[1], kd[2], kd[3]};
;                         *(LAS u32x4*)(set + G2_KDT + d * 80 + seg * 32 + 16) = (u32x4){kd[4], kd[5], kd[6], kd[7]};
;                         if (seg == 0) *(LAS float*)(set + G2_EBL + d * 4) = ebl;
	v_cndmask_b32_e64 v25, v104, 0, s[38:39]
	v_cndmask_b32_e64 v26, 0, v105, s[38:39]
	v_cndmask_b32_e64 v102, v26, v25, s[48:49]
	v_add_f32_e32 v16, v16, v102
	v_exp_f32_e32 v108, v16
	v_add_f32_e32 v16, v110, v102
	v_exp_f32_e32 v109, v16
	v_add_f32_e32 v16, v104, v105
	v_rcp_f32_e32 v104, v108
	v_lshlrev_b32_e32 v110, 16, v98
	v_rcp_f32_e32 v105, v109
	v_pk_mul_f32 v[108:109], v[108:109], v[110:111]
	s_nop 0
	v_lshlrev_b32_e32 v101, 16, v101
	v_cvt_pk_bf16_f32 v25, v108, v109
	v_add3_u32 v108, s15, v201, v211
	v_lshlrev_b32_e32 v100, 16, v99
	ds_write_b16 v108, v25
	ds_write_b16_d16_hi v108, v25 offset:272
	v_add_f32_e32 v25, v107, v102
	v_pk_mul_f32 v[98:99], v[104:105], v[100:101]
	v_exp_f32_e32 v100, v25
	v_add_f32_e32 v25, v106, v102
	v_exp_f32_e32 v101, v25
	v_lshlrev_b32_e32 v107, 16, v96
	v_lshlrev_b32_e32 v106, 16, v94
	v_rcp_f32_e32 v104, v100
	v_rcp_f32_e32 v105, v101
	v_pk_mul_f32 v[100:101], v[100:101], v[106:107]
	v_cvt_pk_bf16_f32 v26, v98, v99
	v_cvt_pk_bf16_f32 v25, v100, v101
	ds_write_b16 v232, v26
	ds_write_b16_d16_hi v232, v26 offset:272
	ds_write_b16 v108, v25 offset:544
	ds_write_b16_d16_hi v108, v25 offset:816
	v_add_f32_e32 v25, v103, v102
	v_exp_f32_e32 v16, v16
	v_exp_f32_e32 v30, v25
	v_add_f32_e32 v25, v31, v102
	v_exp_f32_e32 v31, v25
	s_nop 0
	v_lshlrev_b32_e32 v97, 16, v97
	v_lshlrev_b32_e32 v96, 16, v95
	v_pk_mul_f32 v[94:95], v[104:105], v[96:97]
	v_pk_mul_f32 v[98:99], v[16:17], v[98:99] op_sel_hi:[0,1]
	v_cvt_pk_bf16_f32 v26, v94, v95
	v_pk_mul_f32 v[94:95], v[16:17], v[94:95] op_sel_hi:[0,1]
	v_lshlrev_b32_e32 v97, 16, v92
	v_lshlrev_b32_e32 v96, 16, v90
	v_cvt_pk_bf16_f32 v98, v98, v99
	v_cvt_pk_bf16_f32 v99, v94, v95
	v_rcp_f32_e32 v94, v30
	v_rcp_f32_e32 v95, v31
	v_pk_mul_f32 v[30:31], v[30:31], v[96:97]
	ds_write_b16 v232, v26 offset:544
	ds_write_b16_d16_hi v232, v26 offset:816
	v_cvt_pk_bf16_f32 v25, v30, v31
	ds_write_b16 v108, v25 offset:1088
	ds_write_b16_d16_hi v108, v25 offset:1360
	v_add_f32_e32 v25, v28, v102
	v_exp_f32_e32 v26, v25
	v_add_f32_e32 v25, v27, v102
	v_exp_f32_e32 v27, v25
	s_nop 0
	v_lshlrev_b32_e32 v31, 16, v93
	v_lshlrev_b32_e32 v30, 16, v91
	v_pk_mul_f32 v[30:31], v[94:95], v[30:31]
	v_rcp_f32_e32 v28, v26
	v_cvt_pk_bf16_f32 v29, v30, v31
	v_pk_mul_f32 v[30:31], v[16:17], v[30:31] op_sel_hi:[0,1]
	v_cvt_pk_bf16_f32 v100, v30, v31
	ds_write_b16 v232, v29 offset:1088
	ds_write_b16_d16_hi v232, v29 offset:1360
	v_rcp_f32_e32 v29, v27
	v_lshlrev_b32_e32 v31, 16, v84
	v_lshlrev_b32_e32 v30, 16, v82
	v_pk_mul_f32 v[26:27], v[26:27], v[30:31]
	v_add_f32_e32 v24, v24, v102
	v_cvt_pk_bf16_f32 v25, v26, v27
	v_add_f32_e32 v23, v23, v102
	s_nop 0
	v_lshlrev_b32_e32 v27, 16, v85
	v_lshlrev_b32_e32 v26, 16, v83
	ds_write_b16 v108, v25 offset:1632
	ds_write_b16_d16_hi v108, v25 offset:1904
	v_exp_f32_e32 v24, v24
	v_exp_f32_e32 v25, v23
	v_pk_mul_f32 v[26:27], v[28:29], v[26:27]
	s_nop 0
	v_lshlrev_b32_e32 v29, 16, v88
	v_cvt_pk_bf16_f32 v28, v26, v27
	v_pk_mul_f32 v[26:27], v[16:17], v[26:27] op_sel_hi:[0,1]
	ds_write_b16 v232, v28 offset:1632
	ds_write_b16_d16_hi v232, v28 offset:1904
	v_lshlrev_b32_e32 v28, 16, v86
	v_cvt_pk_bf16_f32 v101, v26, v27
	v_rcp_f32_e32 v26, v24
	v_rcp_f32_e32 v27, v25
	v_pk_mul_f32 v[24:25], v[24:25], v[28:29]
	v_add_f32_e32 v22, v22, v102
	v_cvt_pk_bf16_f32 v23, v24, v25
	v_add_f32_e32 v21, v21, v102
	ds_write_b16 v108, v23 offset:2176
	ds_write_b16_d16_hi v108, v23 offset:2448
	v_exp_f32_e32 v22, v22
	v_exp_f32_e32 v23, v21
	s_nop 0
	v_lshlrev_b32_e32 v25, 16, v89
	v_lshlrev_b32_e32 v24, 16, v87
	v_pk_mul_f32 v[24:25], v[26:27], v[24:25]
	v_lshlrev_b32_e32 v29, 16, v80
	v_cvt_pk_bf16_f32 v26, v24, v25
	v_lshlrev_b32_e32 v28, 16, v78
	ds_write_b16 v232, v26 offset:2176
	ds_write_b16_d16_hi v232, v26 offset:2448
	v_rcp_f32_e32 v26, v22
	v_rcp_f32_e32 v27, v23
	v_pk_mul_f32 v[22:23], v[22:23], v[28:29]
	v_add_f32_e32 v20, v20, v102
	v_cvt_pk_bf16_f32 v21, v22, v23
	v_add_f32_e32 v19, v19, v102
	ds_write_b16 v108, v21 offset:2720
	ds_write_b16_d16_hi v108, v21 offset:2992
	v_exp_f32_e32 v20, v20
	v_exp_f32_e32 v21, v19
	s_nop 0
	v_lshlrev_b32_e32 v23, 16, v81
	v_lshlrev_b32_e32 v22, 16, v79
	v_pk_mul_f32 v[22:23], v[26:27], v[22:23]
	v_pk_mul_f32 v[24:25], v[16:17], v[24:25] op_sel_hi:[0,1]
	v_cvt_pk_bf16_f32 v26, v22, v23
	v_pk_mul_f32 v[22:23], v[16:17], v[22:23] op_sel_hi:[0,1]
	v_cvt_pk_bf16_f32 v24, v24, v25
	v_cvt_pk_bf16_f32 v25, v22, v23
	v_rcp_f32_e32 v22, v20
	v_rcp_f32_e32 v23, v21
	ds_write_b16 v232, v26 offset:2720
	ds_write_b16_d16_hi v232, v26 offset:2992
	v_lshlrev_b32_e32 v27, 16, v76
	v_lshlrev_b32_e32 v26, 16, v74
	v_pk_mul_f32 v[20:21], v[20:21], v[26:27]
	v_add_f32_e32 v18, v18, v102
	v_cvt_pk_bf16_f32 v19, v20, v21
	s_nop 0
	v_lshlrev_b32_e32 v21, 16, v77
	v_lshlrev_b32_e32 v20, 16, v75
	v_pk_mul_f32 v[20:21], v[22:23], v[20:21]
	ds_write_b16 v108, v19 offset:3264
	ds_write_b16_d16_hi v108, v19 offset:3536
	v_cvt_pk_bf16_f32 v22, v20, v21
	v_pk_mul_f32 v[20:21], v[16:17], v[20:21] op_sel_hi:[0,1]
	v_add_f32_e32 v17, v17, v102
	v_exp_f32_e32 v18, v18
	v_exp_f32_e32 v19, v17
	v_cvt_pk_bf16_f32 v26, v20, v21
	ds_write_b16 v232, v22 offset:3264
	ds_write_b16_d16_hi v232, v22 offset:3536
	v_rcp_f32_e32 v20, v18
	v_rcp_f32_e32 v21, v19
	v_lshlrev_b32_e32 v23, 16, v72
	v_lshlrev_b32_e32 v22, 16, v70
	v_pk_mul_f32 v[18:19], v[18:19], v[22:23]
	s_nop 0
	v_cvt_pk_bf16_f32 v17, v18, v19
	s_nop 0
	v_lshlrev_b32_e32 v19, 16, v73
	v_lshlrev_b32_e32 v18, 16, v71
	v_pk_mul_f32 v[18:19], v[20:21], v[18:19]
	s_nop 0
	v_cvt_pk_bf16_f32 v20, v18, v19
	v_pk_mul_f32 v[18:19], v[16:17], v[18:19] op_sel_hi:[0,1]
	ds_write_b16 v108, v17 offset:3808
	ds_write_b16_d16_hi v108, v17 offset:4080
	ds_write_b16 v232, v20 offset:3808
	ds_write_b16_d16_hi v232, v20 offset:4080
	v_add3_u32 v17, s15, v203, v204
	v_cvt_pk_bf16_f32 v27, v18, v19
	ds_write_b128 v17, v[98:101] offset:8704
	ds_write_b128 v17, v[24:27] offset:8720
	s_and_saveexec_b64 s[6:7], s[38:39]
	s_cbranch_execz .LBB0_219
	v_add_u32_e32 v17, s15, v202
	ds_write_b32 v17, v16 offset:41984
	s_branch .LBB0_219
